# G2 phase start: the first k-step's eight LDS-DMA loads are issued before the row-factor table fill (its cold global loads and workgroup barrier now overlap the tile fetch)
# speedup vs baseline: 1.0081x; 1.0026x over previous
.LBB0_567:
	s_andn2_b64 vcc, exec, s[10:11]
	s_cbranch_vccnz .LBB0_610
	v_mov_b32_e32 v17, v232
	s_and_b64 vcc, exec, s[6:7]
	v_readfirstlane_b32 s8, v17
	s_cbranch_vccnz .LBB0_610
	v_lshlrev_b32_e32 v2, 4, v17
	v_add_u32_e32 v3, 0x2000, v2
	v_ashrrev_i32_e32 v0, 31, v3
	v_lshrrev_b32_e32 v0, 22, v0
	v_add_u32_e32 v0, v3, v0
	v_ashrrev_i32_e32 v0, 10, v0
	v_mul_i32_i24_e32 v4, 0x400, v0
	v_sub_u32_e32 v3, v3, v4
	v_lshrrev_b32_e32 v4, 4, v3
	v_bitop3_b32 v3, v4, v3, 32 bitop3:0x6c
	v_ashrrev_i32_e32 v4, 31, v3
	v_lshrrev_b32_e32 v4, 26, v4
	v_add_u32_e32 v4, v3, v4
	v_lshlrev_b32_e32 v5, 3, v0
	v_ashrrev_i32_e32 v10, 6, v4
	v_and_b32_e32 v5, -16, v5
	v_add_u32_e32 v5, v10, v5
	v_and_b32_e32 v6, 3, v10
	s_mov_b32 s4, 0x1fffe0
	v_lshrrev_b32_e32 v7, 2, v5
	v_lshlrev_b32_e32 v8, 1, v5
	v_and_b32_e32 v4, 0xc0, v4
	v_and_or_b32 v6, v5, s4, v6
	v_and_b32_e32 v7, 4, v7
	v_and_b32_e32 v8, 24, v8
	v_sub_u32_e32 v3, v3, v4
	v_or3_b32 v6, v6, v7, v8
	v_lshlrev_b32_e32 v7, 5, v0
	v_ashrrev_i16_sdwa v3, v247, sext(v3) dst_sel:DWORD dst_unused:UNUSED_PAD src0_sel:DWORD src1_sel:BYTE_0
	v_and_b32_e32 v11, 32, v7
	v_bfe_i32 v12, v3, 0, 16
	v_add_u32_e32 v3, v11, v12
	v_lshlrev_b32_e32 v4, 1, v3
	s_movk_i32 s5, 0xe00
	v_lshl_add_u32 v192, v6, 11, v4
	v_mul_lo_u32 v4, v5, s5
	v_add_lshl_u32 v202, v3, v4, 1
	v_bfe_i32 v3, v17, 27, 1
	v_lshrrev_b32_e32 v3, 22, v3
	v_add_u32_e32 v3, v2, v3
	v_and_b32_e32 v3, 0xfffffc00, v3
	v_sub_u32_e32 v2, v2, v3
	v_lshrrev_b32_e32 v3, 4, v2
	v_bitop3_b32 v3, v3, v2, 32 bitop3:0x6c
	v_ashrrev_i32_e32 v2, 31, v2
	v_lshrrev_b32_e32 v2, 26, v2
	v_add_u32_e32 v2, v3, v2
	v_ashrrev_i32_e32 v13, 6, v2
	v_ashrrev_i32_e32 v2, 31, v17
	v_lshrrev_b32_e32 v2, 26, v2
	v_add_u32_e32 v2, v17, v2
	v_ashrrev_i32_e32 v14, 6, v2
	v_lshlrev_b32_e32 v2, 3, v14
	v_and_b32_e32 v2, -16, v2
	v_add_u32_e32 v2, v13, v2
	v_and_b32_e32 v4, 3, v13
	v_lshrrev_b32_e32 v5, 2, v2
	v_lshlrev_b32_e32 v6, 1, v2
	v_and_or_b32 v4, v2, s4, v4
	v_and_b32_e32 v5, 4, v5
	v_and_b32_e32 v6, 24, v6
	v_or3_b32 v4, v4, v5, v6
	v_lshlrev_b32_e32 v5, 5, v14
	v_and_b32_e32 v15, 32, v5
	v_mul_i32_i24_e32 v5, 64, v13
	v_sub_u32_e32 v3, v3, v5
	s_ashr_i32 s10, s8, 6
	v_ashrrev_i16_sdwa v3, v247, sext(v3) dst_sel:DWORD dst_unused:UNUSED_PAD src0_sel:DWORD src1_sel:BYTE_0
	s_ashr_i32 s9, s8, 8
	s_lshl_b32 s40, s10, 10
	v_bfe_i32 v16, v3, 0, 16
	v_mul_lo_u32 v2, v2, s5
	v_readlane_b32 s4, v255, 41
	v_add_u32_e32 v3, v15, v16
	v_readlane_b32 s5, v255, 42
	s_add_u32 s34, s44, s4
	v_lshlrev_b32_e32 v5, 1, v3
	s_addc_u32 s35, s45, s5
	s_add_i32 s41, s40, 0
	v_lshl_add_u32 v204, v4, 11, v5
	s_add_i32 m0, s41, 0x10000
	v_readlane_b32 s4, v255, 40
	global_load_lds_dwordx4 v204, s[34:35]
	s_add_i32 m0, s41, 0x12000
	s_add_u32 s12, s34, 0x40000
	global_load_lds_dwordx4 v192, s[34:35]
	s_addc_u32 s13, s35, 0
	s_add_i32 m0, s41, 0x14000
	v_add_lshl_u32 v206, v3, v2, 1
	global_load_lds_dwordx4 v204, s[12:13]
	s_add_i32 m0, s41, 0x16000
	s_add_u32 s30, s42, s4
	v_readlane_b32 s4, v255, 39
	s_addc_u32 s31, s43, s4
	s_add_i32 s51, s41, 0x2000
	global_load_lds_dwordx4 v192, s[12:13]
	s_mov_b32 m0, s41
	s_add_u32 s12, s30, 0xe0000
	global_load_lds_dwordx4 v206, s[30:31]
	s_mov_b32 m0, s51
	s_addc_u32 s13, s31, 0
	s_add_i32 s55, s41, 0x4000
	global_load_lds_dwordx4 v202, s[30:31]
	s_mov_b32 m0, s55
	s_add_i32 s56, s41, 0x6000
	global_load_lds_dwordx4 v206, s[12:13]
	s_mov_b32 m0, s56
	v_mov_b32_e32 v205, v1
	global_load_lds_dwordx4 v202, s[12:13]
	v_mov_b32_e32 v193, v1
	v_mov_b32_e32 v207, v1
	v_mov_b32_e32 v203, v1
	s_movk_i32 s98, 0x100
	v_readlane_b32 s100, v255, 7
	v_cmp_gt_i32_e32 vcc, s98, v241
	v_readlane_b32 s101, v255, 8
	s_and_b64 s[100:101], s[100:101], vcc
	s_and_saveexec_b64 s[98:99], s[100:101]
	s_cbranch_execz .LBB0_570
	s_load_dwordx2 s[100:101], s[0:1], 0x90
	v_readlane_b32 vcc_lo, v255, 47
	s_waitcnt lgkmcnt(0)
	s_add_u32 s100, s100, 0xef00000
	s_addc_u32 s101, s101, 0
	v_lshl_add_u32 v22, vcc_lo, 8, v241
	v_ashrrev_i32_e32 v23, 31, v22
	v_lshlrev_b64 v[22:23], 5, v[22:23]
	v_lshl_add_u64 v[26:27], s[100:101], 0, v[22:23]
	global_load_dwordx4 v[22:25], v[26:27], off
	s_nop 0
	global_load_dwordx4 v[26:29], v[26:27], off offset:16
	s_waitcnt vmcnt(1)
	v_mov_b32_e32 v30, v22
	s_waitcnt vmcnt(0)
	v_mov_b32_e32 v31, v26
	v_mov_b32_e32 v26, v23
	v_mov_b32_e32 v22, v24
	v_mov_b32_e32 v23, v28
	v_mov_b32_e32 v28, v25
	v_pk_add_f32 v[24:25], v[30:31], v[26:27]
	v_pk_add_f32 v[22:23], v[22:23], v[28:29]
	s_nop 0
	v_pk_add_f32 v[22:23], v[24:25], v[22:23]
	s_nop 0
	v_add_f32_e32 v20, v22, v23
	v_fmamk_f32 v20, v20, 0x3b000000, v233
	v_mul_f32_e32 v22, 0x4b800000, v20
	v_cmp_gt_f32_e32 vcc, s82, v20
	s_nop 1
	v_cndmask_b32_e32 v20, v20, v22, vcc
	v_rsq_f32_e32 v20, v20
	v_lshl_add_u32 v22, v241, 2, 0
	v_add_u32_e32 v22, 0x20400, v22
	v_mul_f32_e32 v23, 0x45800000, v20
	v_cndmask_b32_e32 v20, v20, v23, vcc
	ds_write_b32 v22, v20
.LBB0_570:
	s_or_b64 exec, exec, s[98:99]
	s_waitcnt lgkmcnt(0)
	s_barrier
	s_cmp_eq_u32 s9, 1
	v_lshl_add_u64 v[8:9], s[34:35], 0, v[204:205]
	v_lshl_add_u64 v[6:7], s[34:35], 0, v[192:193]
	v_lshl_add_u64 v[2:3], s[30:31], 0, v[206:207]
	s_cselect_b64 s[20:21], -1, 0
	s_cmp_lg_u32 s9, 1
	v_lshl_add_u64 v[4:5], s[30:31], 0, v[202:203]
	s_cbranch_scc1 .LBB0_573
	s_barrier
